# top-256 search count loop: e32 v_cmp/v_addc through VCC instead of e64 pairs through SGPRs
# speedup vs baseline: 1.0019x; 1.0004x over previous
; DI int wave_sum_i(int x) { x = row_sum16(x); return __builtin_amdgcn_readlane(x, 0) + __builtin_amdgcn_readlane(x, 16) + __builtin_amdgcn_readlane(x, 32) + __builtin_amdgcn_readlane(x, 48); }
; DI int cnt4_ge(unsigned k0, unsigned k1, unsigned k2, unsigned k3, unsigned cand, int cl) {
;     unsigned long long m0, m1, m2, m3;
;     asm volatile("v_cmp_le_u32_e64 %1, %9, %5\n\tv_cmp_le_u32_e64 %2, %9, %6\n\tv_cmp_le_u32_e64 %3, %9, %7\n\tv_cmp_le_u32_e64 %4, %9, %8\n\t"
;                  "v_addc_co_u32_e64 %0, %1, 0, %0, %1\n\tv_addc_co_u32_e64 %0, %2, 0, %0, %2\n\tv_addc_co_u32_e64 %0, %3, 0, %0, %3\n\tv_addc_co_u32_e64 %0, %4, 0, %0, %4"
;                  : "+v"(cl), "=&s"(m0), "=&s"(m1), "=&s"(m2), "=&s"(m3) : "v"(k0), "v"(k1), "v"(k2), "v"(k3), "s"(cand));
;     return cl;
; }
; DI void index_unit(Frame& F, int b, int t0) {
;     ...
;             const unsigned cand = res | (1u << bit);
;             int cl = 0;
; #pragma unroll
;             for (int gq = 0; gq < 8; ++gq) if (8 * gq < nreg) {
; #pragma unroll
;                 for (int i = 8 * gq; i < 8 * gq + 8; i += 4) cl = cnt4_ge(key[i], key[i + 1], key[i + 2], key[i + 3], cand, cl); }
;             const int cnt = wave_sum_i(cl);
.Lsel_count:
	v_mov_b32_e32 v67, 0
	v_cndmask_b32_e64 v68, 0, 1, s[0:1]
	v_or_b32_e32 v5, v5, v66
	v_cmp_le_u32_e32 vcc, v5, v3
	v_addc_co_u32_e32 v67, vcc, 0, v67, vcc
	v_cmp_le_u32_e32 vcc, v5, v2
	v_addc_co_u32_e32 v67, vcc, 0, v67, vcc
	v_cmp_le_u32_e32 vcc, v5, v1
	v_addc_co_u32_e32 v67, vcc, 0, v67, vcc
	v_cmp_le_u32_e32 vcc, v5, v0
	v_addc_co_u32_e32 v67, vcc, 0, v67, vcc
	v_cmp_ne_u32_e64 s[82:83], 1, v68
	v_cmp_le_u32_e32 vcc, v5, v8
	v_addc_co_u32_e32 v67, vcc, 0, v67, vcc
	v_cmp_le_u32_e32 vcc, v5, v6
	v_addc_co_u32_e32 v67, vcc, 0, v67, vcc
	v_cmp_le_u32_e32 vcc, v5, v11
	v_addc_co_u32_e32 v67, vcc, 0, v67, vcc
	v_cmp_le_u32_e32 vcc, v5, v7
	v_addc_co_u32_e32 v67, vcc, 0, v67, vcc
	s_andn2_b64 vcc, exec, s[0:1]
	s_cbranch_vccz .LBB0_346
	v_cndmask_b32_e64 v68, 0, 1, s[4:5]
	v_cmp_ne_u32_e64 s[80:81], 1, v68
	s_andn2_b64 vcc, exec, s[4:5]
	s_cbranch_vccz .LBB0_347

; DI int wave_sum_i(int x) { x = row_sum16(x); return __builtin_amdgcn_readlane(x, 0) + __builtin_amdgcn_readlane(x, 16) + __builtin_amdgcn_readlane(x, 32) + __builtin_amdgcn_readlane(x, 48); }
; DI int cnt4_ge(unsigned k0, unsigned k1, unsigned k2, unsigned k3, unsigned cand, int cl) {
;     unsigned long long m0, m1, m2, m3;
;     asm volatile("v_cmp_le_u32_e64 %1, %9, %5\n\tv_cmp_le_u32_e64 %2, %9, %6\n\tv_cmp_le_u32_e64 %3, %9, %7\n\tv_cmp_le_u32_e64 %4, %9, %8\n\t"
;                  "v_addc_co_u32_e64 %0, %1, 0, %0, %1\n\tv_addc_co_u32_e64 %0, %2, 0, %0, %2\n\tv_addc_co_u32_e64 %0, %3, 0, %0, %3\n\tv_addc_co_u32_e64 %0, %4, 0, %0, %4"
;                  : "+v"(cl), "=&s"(m0), "=&s"(m1), "=&s"(m2), "=&s"(m3) : "v"(k0), "v"(k1), "v"(k2), "v"(k3), "s"(cand));
;     return cl;
; }
; DI void index_unit(Frame& F, int b, int t0) {
;     ...
;             const unsigned cand = res | (1u << bit);
;             int cl = 0;
; #pragma unroll
;             for (int gq = 0; gq < 8; ++gq) if (8 * gq < nreg) {
; #pragma unroll
;                 for (int i = 8 * gq; i < 8 * gq + 8; i += 4) cl = cnt4_ge(key[i], key[i + 1], key[i + 2], key[i + 3], cand, cl); }
;             const int cnt = wave_sum_i(cl);
.LBB0_346:
	v_cmp_le_u32_e32 vcc, v5, v13
	v_addc_co_u32_e32 v67, vcc, 0, v67, vcc
	v_cmp_le_u32_e32 vcc, v5, v9
	v_addc_co_u32_e32 v67, vcc, 0, v67, vcc
	v_cmp_le_u32_e32 vcc, v5, v15
	v_addc_co_u32_e32 v67, vcc, 0, v67, vcc
	v_cmp_le_u32_e32 vcc, v5, v10
	v_addc_co_u32_e32 v67, vcc, 0, v67, vcc
	s_nop 0
	v_cmp_le_u32_e32 vcc, v5, v17
	v_addc_co_u32_e32 v67, vcc, 0, v67, vcc
	v_cmp_le_u32_e32 vcc, v5, v12
	v_addc_co_u32_e32 v67, vcc, 0, v67, vcc
	v_cmp_le_u32_e32 vcc, v5, v19
	v_addc_co_u32_e32 v67, vcc, 0, v67, vcc
	v_cmp_le_u32_e32 vcc, v5, v14
	v_addc_co_u32_e32 v67, vcc, 0, v67, vcc
	v_cndmask_b32_e64 v68, 0, 1, s[4:5]
	v_cmp_ne_u32_e64 s[80:81], 1, v68
	s_andn2_b64 vcc, exec, s[4:5]
	s_cbranch_vccnz .LBB0_341
.LBB0_347:
	v_cmp_le_u32_e32 vcc, v5, v21
	v_addc_co_u32_e32 v67, vcc, 0, v67, vcc
	v_cmp_le_u32_e32 vcc, v5, v16
	v_addc_co_u32_e32 v67, vcc, 0, v67, vcc
	v_cmp_le_u32_e32 vcc, v5, v23
	v_addc_co_u32_e32 v67, vcc, 0, v67, vcc
	v_cmp_le_u32_e32 vcc, v5, v18
	v_addc_co_u32_e32 v67, vcc, 0, v67, vcc
	s_nop 0
	v_cmp_le_u32_e32 vcc, v5, v25
	v_addc_co_u32_e32 v67, vcc, 0, v67, vcc
	v_cmp_le_u32_e32 vcc, v5, v20
	v_addc_co_u32_e32 v67, vcc, 0, v67, vcc
	v_cmp_le_u32_e32 vcc, v5, v27
	v_addc_co_u32_e32 v67, vcc, 0, v67, vcc
	v_cmp_le_u32_e32 vcc, v5, v22
	v_addc_co_u32_e32 v67, vcc, 0, v67, vcc
	v_cndmask_b32_e64 v68, 0, 1, s[6:7]
	v_cmp_ne_u32_e64 s[78:79], 1, v68
	s_andn2_b64 vcc, exec, s[6:7]
	s_cbranch_vccnz .LBB0_342
.LBB0_348:
	v_cmp_le_u32_e32 vcc, v5, v29
	v_addc_co_u32_e32 v67, vcc, 0, v67, vcc
	v_cmp_le_u32_e32 vcc, v5, v24
	v_addc_co_u32_e32 v67, vcc, 0, v67, vcc
	v_cmp_le_u32_e32 vcc, v5, v31
	v_addc_co_u32_e32 v67, vcc, 0, v67, vcc
	v_cmp_le_u32_e32 vcc, v5, v26
	v_addc_co_u32_e32 v67, vcc, 0, v67, vcc
	s_nop 0
	v_cmp_le_u32_e32 vcc, v5, v33
	v_addc_co_u32_e32 v67, vcc, 0, v67, vcc
	v_cmp_le_u32_e32 vcc, v5, v28
	v_addc_co_u32_e32 v67, vcc, 0, v67, vcc
	v_cmp_le_u32_e32 vcc, v5, v35
	v_addc_co_u32_e32 v67, vcc, 0, v67, vcc
	v_cmp_le_u32_e32 vcc, v5, v30
	v_addc_co_u32_e32 v67, vcc, 0, v67, vcc
	v_cndmask_b32_e64 v68, 0, 1, s[8:9]
	v_cmp_ne_u32_e64 s[76:77], 1, v68
	s_andn2_b64 vcc, exec, s[8:9]
	s_cbranch_vccnz .LBB0_343
.LBB0_349:
	v_cmp_le_u32_e32 vcc, v5, v37
	v_addc_co_u32_e32 v67, vcc, 0, v67, vcc
	v_cmp_le_u32_e32 vcc, v5, v32
	v_addc_co_u32_e32 v67, vcc, 0, v67, vcc
	v_cmp_le_u32_e32 vcc, v5, v39
	v_addc_co_u32_e32 v67, vcc, 0, v67, vcc
	v_cmp_le_u32_e32 vcc, v5, v34
	v_addc_co_u32_e32 v67, vcc, 0, v67, vcc
	s_nop 0
	v_cmp_le_u32_e32 vcc, v5, v41
	v_addc_co_u32_e32 v67, vcc, 0, v67, vcc
	v_cmp_le_u32_e32 vcc, v5, v36
	v_addc_co_u32_e32 v67, vcc, 0, v67, vcc
	v_cmp_le_u32_e32 vcc, v5, v43
	v_addc_co_u32_e32 v67, vcc, 0, v67, vcc
	v_cmp_le_u32_e32 vcc, v5, v38
	v_addc_co_u32_e32 v67, vcc, 0, v67, vcc
	v_cndmask_b32_e64 v68, 0, 1, s[10:11]
	v_cmp_ne_u32_e64 s[74:75], 1, v68
	s_andn2_b64 vcc, exec, s[10:11]
	s_cbranch_vccnz .LBB0_344
.LBB0_350:
	v_cmp_le_u32_e32 vcc, v5, v45
	v_addc_co_u32_e32 v67, vcc, 0, v67, vcc
	v_cmp_le_u32_e32 vcc, v5, v40
	v_addc_co_u32_e32 v67, vcc, 0, v67, vcc
	v_cmp_le_u32_e32 vcc, v5, v47
	v_addc_co_u32_e32 v67, vcc, 0, v67, vcc
	v_cmp_le_u32_e32 vcc, v5, v42
	v_addc_co_u32_e32 v67, vcc, 0, v67, vcc
	s_nop 0
	v_cmp_le_u32_e32 vcc, v5, v49
	v_addc_co_u32_e32 v67, vcc, 0, v67, vcc
	v_cmp_le_u32_e32 vcc, v5, v44
	v_addc_co_u32_e32 v67, vcc, 0, v67, vcc
	v_cmp_le_u32_e32 vcc, v5, v51
	v_addc_co_u32_e32 v67, vcc, 0, v67, vcc
	v_cmp_le_u32_e32 vcc, v5, v46
	v_addc_co_u32_e32 v67, vcc, 0, v67, vcc
	v_cndmask_b32_e64 v68, 0, 1, s[12:13]
	v_cmp_ne_u32_e64 s[72:73], 1, v68
	s_andn2_b64 vcc, exec, s[12:13]
	s_cbranch_vccnz .LBB0_345
.LBB0_351:
	v_cmp_le_u32_e32 vcc, v5, v53
	v_addc_co_u32_e32 v67, vcc, 0, v67, vcc
	v_cmp_le_u32_e32 vcc, v5, v48
	v_addc_co_u32_e32 v67, vcc, 0, v67, vcc
	v_cmp_le_u32_e32 vcc, v5, v55
	v_addc_co_u32_e32 v67, vcc, 0, v67, vcc
	v_cmp_le_u32_e32 vcc, v5, v50
	v_addc_co_u32_e32 v67, vcc, 0, v67, vcc
	s_nop 0
	v_cmp_le_u32_e32 vcc, v5, v57
	v_addc_co_u32_e32 v67, vcc, 0, v67, vcc
	v_cmp_le_u32_e32 vcc, v5, v52
	v_addc_co_u32_e32 v67, vcc, 0, v67, vcc
	v_cmp_le_u32_e32 vcc, v5, v59
	v_addc_co_u32_e32 v67, vcc, 0, v67, vcc
	v_cmp_le_u32_e32 vcc, v5, v54
	v_addc_co_u32_e32 v67, vcc, 0, v67, vcc
	v_cndmask_b32_e64 v68, 0, 1, s[14:15]
	v_cmp_ne_u32_e64 s[70:71], 1, v68
	s_andn2_b64 vcc, exec, s[14:15]
	s_cbranch_vccnz .LBB0_338
.LBB0_352:
	v_cmp_le_u32_e32 vcc, v5, v61
	v_addc_co_u32_e32 v67, vcc, 0, v67, vcc
	v_cmp_le_u32_e32 vcc, v5, v56
	v_addc_co_u32_e32 v67, vcc, 0, v67, vcc
	v_cmp_le_u32_e32 vcc, v5, v63
	v_addc_co_u32_e32 v67, vcc, 0, v67, vcc
	v_cmp_le_u32_e32 vcc, v5, v58
	v_addc_co_u32_e32 v67, vcc, 0, v67, vcc
	s_nop 0
	v_cmp_le_u32_e32 vcc, v5, v64
	v_addc_co_u32_e32 v67, vcc, 0, v67, vcc
	v_cmp_le_u32_e32 vcc, v5, v60
	v_addc_co_u32_e32 v67, vcc, 0, v67, vcc
	v_cmp_le_u32_e32 vcc, v5, v65
	v_addc_co_u32_e32 v67, vcc, 0, v67, vcc
	v_cmp_le_u32_e32 vcc, v5, v62
	v_addc_co_u32_e32 v67, vcc, 0, v67, vcc
	s_branch .LBB0_338
